# layer-0 expert tables are fp4-quantised in layer 0's B1 phase (hosted, overlapped with MoBA like tables 1-3) instead of in phase 0
# speedup vs baseline: 1.0054x; 1.0054x over previous
; __device__ __forceinline__ int otid() { int t = threadIdx.x; asm volatile("" : "+v"(t)); return t; }
; __device__ void quant_rows(const float* src, unsigned char* dst, float* scales, int row_begin, int nrows) {
;   const int tid_ = otid();
;   const int lane = tid_ & 63, w = tid_ >> 6;
;   for (int row = row_begin + blockIdx.x * 4 + w; row < nrows; row += gridDim.x * 4) {
;     const f32x4* sp = (const f32x4*)(src + (size_t)row * 1024) + lane * 4;
;     f32x4 v[4];
; __global__ void __launch_bounds__(256, 2) fwd_kernel(P p) {
;     ...
;   quant_rows(p.peer_u, (unsigned char*)(ws + OFF_U), (float*)(ws + OFF_V), 0, 16384);
.LBB0_21:
	s_or_b64 exec, exec, s[0:1]
	v_mov_b32_e32 v1, v208
	s_lshl_b32 s0, s26, 2
	v_ashrrev_i32_e32 v3, 6, v1
	v_writelane_b32 v255, s0, 20
	v_add_u32_e32 v4, s0, v3
	s_movk_i32 s0, 0
	v_cmp_gt_i32_e32 vcc, s0, v4
	v_mbcnt_lo_u32_b32 v110, -1, 0
	s_and_saveexec_b64 s[12:13], vcc
	s_cbranch_execz .LBB0_26
	v_and_b32_e32 v5, 63, v1
	v_readlane_b32 s16, v255, 8
	v_lshlrev_b32_e32 v8, 6, v5
	v_mov_b32_e32 v9, 0
	v_readlane_b32 s20, v255, 12
	v_readlane_b32 s21, v255, 13
	s_add_u32 s14, s8, 0xba84000
	v_readlane_b32 s17, v255, 9
	v_lshl_add_u64 v[6:7], s[20:21], 0, v[8:9]
	v_mbcnt_hi_u32_b32 v8, -1, v110
	v_and_b32_e32 v3, 64, v8
	v_xor_b32_e32 v1, 1, v8
	v_add_u32_e32 v13, 64, v3
	v_cmp_lt_i32_e32 vcc, v1, v13
	v_xor_b32_e32 v3, 2, v8
	v_xor_b32_e32 v10, 4, v8
	v_cndmask_b32_e32 v1, v8, v1, vcc
	v_cmp_lt_i32_e32 vcc, v3, v13
	v_xor_b32_e32 v11, 8, v8
	v_xor_b32_e32 v12, 16, v8
	v_cndmask_b32_e32 v3, v8, v3, vcc
	v_cmp_lt_i32_e32 vcc, v10, v13
	v_xor_b32_e32 v14, 32, v8
	s_mov_b64 s[0:1], 0x3a84000
	v_cndmask_b32_e32 v10, v8, v10, vcc
	v_cmp_lt_i32_e32 vcc, v11, v13
	s_addc_u32 s15, s9, 0
	v_lshlrev_b32_e32 v1, 2, v1
	v_cndmask_b32_e32 v11, v8, v11, vcc
	v_cmp_lt_i32_e32 vcc, v12, v13
	v_lshlrev_b32_e32 v3, 2, v3
	v_lshlrev_b32_e32 v10, 2, v10
	v_cndmask_b32_e32 v12, v8, v12, vcc
	v_cmp_lt_i32_e32 vcc, v14, v13
	v_lshlrev_b32_e32 v11, 2, v11
	v_lshlrev_b32_e32 v12, 2, v12
	v_cndmask_b32_e32 v8, v8, v14, vcc
	v_lshlrev_b32_e32 v13, 2, v8
	v_lshlrev_b32_e32 v8, 3, v5
	v_lshl_add_u64 v[8:9], s[8:9], 0, v[8:9]
	v_lshl_add_u64 v[8:9], v[8:9], 0, s[0:1]
	v_cmp_eq_u32_e64 s[0:1], 0, v5
	s_lshl_b32 s2, s78, 2
	s_mov_b64 s[16:17], 0
	s_mov_b32 s3, 0x40c00000
	s_movk_i32 s4, 0x3fff
	v_readlane_b32 s18, v255, 10
	v_readlane_b32 s19, v255, 11
	v_readlane_b32 s22, v255, 14
	v_readlane_b32 s23, v255, 15
	s_branch .LBB0_24

; __device__ __forceinline__ int otid() { int t = threadIdx.x; asm volatile("" : "+v"(t)); return t; }
; __device__ void quant_rows(const float* src, unsigned char* dst, float* scales, int row_begin, int nrows) {
;   const int tid_ = otid();
;   const int lane = tid_ & 63, w = tid_ >> 6;
;   for (int row = row_begin + blockIdx.x * 4 + w; row < nrows; row += gridDim.x * 4) {
;     const f32x4* sp = (const f32x4*)(src + (size_t)row * 1024) + lane * 4;
;     f32x4 v[4];
; __global__ void __launch_bounds__(256, 2) fwd_kernel(P p) {
;     ...
;   quant_rows(p.peer_v, (unsigned char*)(ws + OFF_U) + 4ull * 16384 * 512, (float*)(ws + OFF_V) + 65536, 0, 16384);
.LBB0_26:
	s_or_b64 exec, exec, s[12:13]
	v_mov_b32_e32 v1, v208
	v_readlane_b32 s0, v255, 20
	v_ashrrev_i32_e32 v3, 6, v1
	s_nop 0
	v_add_u32_e32 v4, s0, v3
	s_movk_i32 s0, 0
	v_cmp_gt_i32_e32 vcc, s0, v4
	s_and_saveexec_b64 s[12:13], vcc
	s_cbranch_execz .LBB0_31
	v_and_b32_e32 v5, 63, v1
	v_readlane_b32 s16, v255, 8
	v_lshlrev_b32_e32 v8, 6, v5
	v_mov_b32_e32 v9, 0
	v_readlane_b32 s22, v255, 14
	v_readlane_b32 s23, v255, 15
	s_add_u32 s14, s8, 0xbac4000
	v_readlane_b32 s17, v255, 9
	v_lshl_add_u64 v[6:7], s[22:23], 0, v[8:9]
	v_mbcnt_hi_u32_b32 v8, -1, v110
	v_and_b32_e32 v3, 64, v8
	v_xor_b32_e32 v1, 1, v8
	v_add_u32_e32 v13, 64, v3
	v_cmp_lt_i32_e32 vcc, v1, v13
	v_xor_b32_e32 v3, 2, v8
	v_xor_b32_e32 v10, 4, v8
	v_cndmask_b32_e32 v1, v8, v1, vcc
	v_cmp_lt_i32_e32 vcc, v3, v13
	v_xor_b32_e32 v11, 8, v8
	v_xor_b32_e32 v12, 16, v8
	v_cndmask_b32_e32 v3, v8, v3, vcc
	v_cmp_lt_i32_e32 vcc, v10, v13
	v_xor_b32_e32 v14, 32, v8
	s_mov_b64 s[0:1], 0x5a84000
	v_cndmask_b32_e32 v10, v8, v10, vcc
	v_cmp_lt_i32_e32 vcc, v11, v13
	s_addc_u32 s15, s9, 0
	v_lshlrev_b32_e32 v1, 2, v1
	v_cndmask_b32_e32 v11, v8, v11, vcc
	v_cmp_lt_i32_e32 vcc, v12, v13
	v_lshlrev_b32_e32 v3, 2, v3
	v_lshlrev_b32_e32 v10, 2, v10
	v_cndmask_b32_e32 v12, v8, v12, vcc
	v_cmp_lt_i32_e32 vcc, v14, v13
	v_lshlrev_b32_e32 v11, 2, v11
	v_lshlrev_b32_e32 v12, 2, v12
	v_cndmask_b32_e32 v8, v8, v14, vcc
	v_lshlrev_b32_e32 v13, 2, v8
	v_lshlrev_b32_e32 v8, 3, v5
	v_lshl_add_u64 v[8:9], s[8:9], 0, v[8:9]
	v_lshl_add_u64 v[8:9], v[8:9], 0, s[0:1]
	v_cmp_eq_u32_e64 s[0:1], 0, v5
	s_lshl_b32 s2, s78, 2
	s_mov_b64 s[16:17], 0
	s_mov_b32 s3, 0x40c00000
	s_movk_i32 s4, 0x3fff
	v_readlane_b32 s18, v255, 10
	v_readlane_b32 s19, v255, 11
	v_readlane_b32 s20, v255, 12
	v_readlane_b32 s21, v255, 13
	s_branch .LBB0_29

; __device__ __forceinline__ int otid() { int t = threadIdx.x; asm volatile("" : "+v"(t)); return t; }
; template <int MI, bool SWAP, bool F8 = false>
; __device__ __forceinline__ void gemm_core(const bf16_t* __restrict__ A, int lda, const bf16_t* __restrict__ B, int ldb,
;                                           int K, char* smem, f32x4 (&acc)[MI][4]) {
;   const int tid = otid(), lane = tid & 63, w = tid >> 6, wm = w >> 1, wn = w & 1;
;   const int lr = tid >> 3, lc = tid & 7;
;   const int li = lane & 15, g = lane >> 4;
;   u32x4 ra[MI], rb[4];
;   const bf16_t* ap = A + (size_t)lr * lda + lc * 8;
;   const bf16_t* bp = B + (size_t)lr * ldb + lc * 8;
; #pragma unroll
;   for (int i = 0; i < MI; ++i)
; #pragma unroll
;     for (int j = 0; j < 4; ++j) acc[i][j] = (f32x4){0.f, 0.f, 0.f, 0.f};
;   const int nk = K >> 6;
; #pragma unroll
;   for (int i = 0; i < MI; ++i) ra[i] = *(const u32x4*)(ap + (size_t)(32 * i) * lda);
; #pragma unroll
;   for (int i = 0; i < 4; ++i) rb[i] = *(const u32x4*)(bp + (size_t)(32 * i) * ldb);
;   const int woff = lr * 128 + ((lc ^ (lr & 7)) << 4);
;   const int xrow = (wm * 16 * MI + li) * 128;
;   const int wrow = 32768 + (wn * 32 + li) * 128;
;   for (int kt = 0; kt < nk; ++kt) {
;     __syncthreads();
; #pragma unroll
;     for (int i = 0; i < MI; ++i) *(u32x4*)(smem + woff + i * 4096) = ra[i];
; #pragma unroll
;     for (int i = 0; i < 4; ++i) *(u32x4*)(smem + 32768 + woff + i * 4096) = rb[i];
;     __syncthreads();
;     if (kt + 1 < nk) {
; #pragma unroll
;       for (int i = 0; i < MI; ++i) ra[i] = *(const u32x4*)(ap + (size_t)(32 * i) * lda + (kt + 1) * 64);
; #pragma unroll
;       for (int i = 0; i < 4; ++i) rb[i] = *(const u32x4*)(bp + (size_t)(32 * i) * ldb + (kt + 1) * 64);
;     }
; __global__ void __launch_bounds__(256, 2) fwd_kernel(P p) {
;     ...
;       const int qb = (layer == 0) ? 16384 : 49152, qe = (layer == 0) ? 49152 : 65536;
.LBB0_383:
	v_readlane_b32 s0, v255, 60
	v_readlane_b32 s1, v255, 61
	s_cmp_lg_u32 s0, 0
	s_cselect_b64 s[0:1], -1, 0
	s_and_b64 s[6:7], s[0:1], exec
	s_mov_b32 s6, 0xc000
	s_cselect_b32 s19, 0x10000, s6
	s_cselect_b32 s36, s6, 0
	v_readlane_b32 s6, v255, 38
	v_readlane_b32 s7, v255, 39
	s_or_b64 s[0:1], s[0:1], s[6:7]
	s_and_b64 vcc, exec, s[0:1]
	s_cbranch_vccnz .LBB0_387
	s_add_u32 s6, s12, 0x3884000
	s_addc_u32 s7, s13, 0
	s_add_u32 s8, s12, 0x25a84000
	s_addc_u32 s9, s13, 0
	s_add_u32 s10, s12, 0x2884000
	v_readlane_b32 s0, v255, 53
	s_addc_u32 s11, s13, 0
	v_readlane_b32 s19, v255, 52
	s_mov_b32 s20, s0
	s_mov_b32 s27, 0x60000
	s_movk_i32 s28, 0x2000
	s_movk_i32 s29, 0xffc0
	s_movk_i32 s30, 0x4000
	s_mov_b32 s31, 0x1ffffc0
	v_readlane_b32 s1, v255, 54
.LBB0_385:
	s_ashr_i32 s0, s20, 7
	s_ashr_i32 s1, s0, 31
	s_bfe_u32 s21, s20, 0x40003
	s_lshl_b64 s[22:23], s[0:1], 19
	s_add_u32 s22, s6, s22
	s_waitcnt vmcnt(14)
	v_mov_b32_e32 v92, v208
	s_addc_u32 s23, s7, s23
	s_lshl_b32 s24, s21, 15
	s_add_u32 s22, s22, s24
	v_ashrrev_i32_e32 v2, 3, v92
	v_ashrrev_i32_e32 v3, 31, v2
	s_addc_u32 s23, s23, 0
	s_lshl_b64 s[24:25], s[0:1], 22
	v_lshlrev_b32_e32 v0, 4, v92
	v_lshlrev_b32_e32 v23, 7, v2
	v_xor_b32_e32 v24, v2, v92
	v_lshlrev_b64 v[40:41], 12, v[2:3]
	v_lshlrev_b64 v[2:3], 8, v[2:3]
	s_add_u32 s24, s8, s24
	v_and_b32_e32 v21, 15, v92
	v_lshrrev_b32_e32 v22, 1, v92
	v_and_b32_e32 v0, 0x70, v0
	v_lshl_add_u64 v[2:3], s[22:23], 0, v[2:3]
	s_addc_u32 s23, s9, s25
	s_and_b32 s22, s19, 0x380
	v_lshrrev_b32_e32 v20, 4, v92
	v_and_b32_e32 v93, 7, v92
	v_and_or_b32 v25, v22, s31, v21
	v_and_or_b32 v21, v22, 32, v21
	v_lshlrev_b32_e32 v22, 4, v24
	v_lshl_add_u64 v[2:3], v[2:3], 0, v[0:1]
	s_lshl_b32 s25, s22, 12
	v_bitop3_b32 v20, v20, v93, 3 bitop3:0x6c
	v_and_or_b32 v134, v22, s33, v23
	v_add_co_u32_e32 v22, vcc, s28, v2
	s_add_u32 s24, s24, s25
	v_lshlrev_b32_e32 v94, 7, v25
	v_lshlrev_b32_e32 v95, 7, v21
	v_lshlrev_b32_e32 v20, 4, v20
	v_addc_co_u32_e32 v23, vcc, 0, v3, vcc
	s_addc_u32 s23, s23, 0
	s_lshl_b32 s25, s21, 8
	v_or_b32_e32 v135, v95, v20
	v_or_b32_e32 v136, v94, v20
	v_add_co_u32_e32 v20, vcc, s30, v2
	s_add_u32 s24, s24, s25
	s_nop 0
	v_addc_co_u32_e32 v21, vcc, 0, v3, vcc
	s_movk_i32 s26, 0x6000
	s_addc_u32 s25, s23, 0
	s_waitcnt vmcnt(10)
	v_add_co_u32_e32 v120, vcc, s26, v2
	v_lshl_add_u64 v[40:41], s[24:25], 0, v[40:41]
	s_nop 0
	v_addc_co_u32_e32 v121, vcc, 0, v3, vcc
	s_waitcnt vmcnt(9)
	v_lshl_add_u64 v[124:125], v[40:41], 0, v[0:1]
	v_add_co_u32_e32 v126, vcc, s46, v124
	global_load_dwordx4 v[24:27], v[2:3], off
	s_nop 0
	v_addc_co_u32_e32 v127, vcc, 0, v125, vcc
	s_waitcnt vmcnt(9)
	v_add_co_u32_e32 v128, vcc, s50, v124
	global_load_dwordx4 v[28:31], v[22:23], off
	global_load_dwordx4 v[32:35], v[20:21], off
	global_load_dwordx4 v[36:39], v[120:121], off
	v_addc_co_u32_e32 v129, vcc, 0, v125, vcc
	v_add_co_u32_e32 v132, vcc, s27, v124
	v_bfe_u32 v0, v92, 4, 2
	s_nop 0
	v_addc_co_u32_e32 v133, vcc, 0, v125, vcc
	global_load_dwordx4 v[40:43], v[124:125], off
	global_load_dwordx4 v[44:47], v[126:127], off
	global_load_dwordx4 v[48:51], v[128:129], off
	global_load_dwordx4 v[52:55], v[132:133], off
	s_waitcnt vmcnt(63) expcnt(7) lgkmcnt(15)
	s_barrier
	v_bitop3_b32 v0, v0, v93, 4 bitop3:0x36
	v_lshlrev_b32_e32 v0, 4, v0
	v_or_b32_e32 v137, v95, v0
	v_or_b32_e32 v0, v94, v0
	s_lshl_b64 s[0:1], s[0:1], 21
	s_lshl_b32 s21, s21, 17
	s_add_u32 s0, s10, s0
	s_addc_u32 s1, s11, s1
	s_add_u32 s0, s0, s21
	s_addc_u32 s1, s1, 0
	s_add_u32 s0, s0, s22
	s_addc_u32 s1, s1, 0
	s_add_i32 s20, s20, s78
	s_add_i32 s19, s19, s77
	s_cmpk_lt_i32 s20, 0x200
	s_waitcnt vmcnt(7)
	ds_write_b128 v134, v[24:27]
	s_waitcnt vmcnt(6)
	ds_write_b128 v134, v[28:31] offset:4096
	s_waitcnt vmcnt(5)
	ds_write_b128 v134, v[32:35] offset:8192
	s_waitcnt vmcnt(4)
	ds_write_b128 v134, v[36:39] offset:12288
	s_waitcnt vmcnt(3)
	ds_write_b128 v134, v[40:43] offset:32768
	s_waitcnt vmcnt(2)
	ds_write_b128 v134, v[44:47] offset:36864
	s_waitcnt vmcnt(1)
	ds_write_b128 v134, v[48:51] offset:40960
	s_waitcnt vmcnt(0)
	ds_write_b128 v134, v[52:55] offset:45056
	s_waitcnt lgkmcnt(0)
	s_barrier
	ds_read_b128 v[24:27], v135 offset:32768
	ds_read_b128 v[28:31], v135 offset:34816
	ds_read_b128 v[32:35], v136
	ds_read_b128 v[36:39], v136 offset:2048
	ds_read_b128 v[44:47], v135 offset:40960
	ds_read_b128 v[52:55], v135 offset:43008
	ds_read_b128 v[72:75], v136 offset:4096
	ds_read_b128 v[76:79], v136 offset:6144
	s_waitcnt lgkmcnt(5)
	v_mfma_f32_16x16x32_bf16 v[40:43], v[24:27], v[32:35], 0
	ds_read_b128 v[92:95], v137 offset:32768
	ds_read_b128 v[96:99], v137 offset:34816
	v_mfma_f32_16x16x32_bf16 v[48:51], v[28:31], v[32:35], 0
	s_waitcnt lgkmcnt(5)
	v_mfma_f32_16x16x32_bf16 v[56:59], v[44:47], v[32:35], 0
	s_waitcnt lgkmcnt(4)
	v_mfma_f32_16x16x32_bf16 v[32:35], v[52:55], v[32:35], 0
	v_mfma_f32_16x16x32_bf16 v[60:63], v[24:27], v[36:39], 0
	v_mfma_f32_16x16x32_bf16 v[64:67], v[28:31], v[36:39], 0
	v_mfma_f32_16x16x32_bf16 v[68:71], v[44:47], v[36:39], 0
	v_mfma_f32_16x16x32_bf16 v[36:39], v[52:55], v[36:39], 0
	s_waitcnt lgkmcnt(3)
	v_mfma_f32_16x16x32_bf16 v[80:83], v[24:27], v[72:75], 0
	v_mfma_f32_16x16x32_bf16 v[84:87], v[28:31], v[72:75], 0
	v_mfma_f32_16x16x32_bf16 v[88:91], v[44:47], v[72:75], 0
	v_mfma_f32_16x16x32_bf16 v[72:75], v[52:55], v[72:75], 0
	s_waitcnt lgkmcnt(2)
	v_mfma_f32_16x16x32_bf16 v[24:27], v[24:27], v[76:79], 0
	v_mfma_f32_16x16x32_bf16 v[28:31], v[28:31], v[76:79], 0
	v_mfma_f32_16x16x32_bf16 v[44:47], v[44:47], v[76:79], 0
	v_mfma_f32_16x16x32_bf16 v[76:79], v[52:55], v[76:79], 0
	ds_read_b128 v[52:55], v0
	ds_read_b128 v[100:103], v0 offset:2048
	ds_read_b128 v[108:111], v137 offset:43008
	s_waitcnt lgkmcnt(2)
; template <int MI, bool SWAP, bool F8 = false>
; __device__ __forceinline__ void gemm_core(const bf16_t* __restrict__ A, int lda, const bf16_t* __restrict__ B, int ldb,
;                                           int K, char* smem, f32x4 (&acc)[MI][4]) {
;     ...
;   for (int kt = 0; kt < nk; ++kt) {
;     __syncthreads();
; #pragma unroll
;     for (int i = 0; i < MI; ++i) *(u32x4*)(smem + woff + i * 4096) = ra[i];
; #pragma unroll
;     for (int i = 0; i < 4; ++i) *(u32x4*)(smem + 32768 + woff + i * 4096) = rb[i];
;     __syncthreads();
;     if (kt + 1 < nk) {
; #pragma unroll
;       for (int i = 0; i < MI; ++i) ra[i] = *(const u32x4*)(ap + (size_t)(32 * i) * lda + (kt + 1) * 64);
; #pragma unroll
;       for (int i = 0; i < 4; ++i) rb[i] = *(const u32x4*)(bp + (size_t)(32 * i) * ldb + (kt + 1) * 64);
;     }
;     if (F8) {
;       const int c0 = (g ^ (li & 7)) << 4, c1 = ((4 + g) ^ (li & 7)) << 4;
;       i32x8 wf8[4];
; #pragma unroll
;       for (int j = 0; j < 4; ++j) {
;         const char* rp = smem + wrow + ((j & 1) * 16 + (j >> 1) * 64) * 128;
;         const u32x4 lo = *(const u32x4*)(rp + c0), hi = *(const u32x4*)(rp + c1);
;         wf8[j] = (i32x8){(int)lo.x, (int)lo.y, (int)lo.z, (int)lo.w, (int)hi.x, (int)hi.y, (int)hi.z, (int)hi.w};
;       }
; #pragma unroll
;       for (int i = 0; i < MI; ++i) {
;         const char* rp = smem + xrow + i * 2048;
;         const u32x4 lo = *(const u32x4*)(rp + c0), hi = *(const u32x4*)(rp + c1);
;         const i32x8 xf8 = {(int)lo.x, (int)lo.y, (int)lo.z, (int)lo.w, (int)hi.x, (int)hi.y, (int)hi.z, (int)hi.w};
; #pragma unroll
;         for (int j = 0; j < 4; ++j)
;           acc[i][j] = __builtin_amdgcn_mfma_scale_f32_16x16x128_f8f6f4(wf8[j], xf8, acc[i][j], 0, 0, 0, 0x77777777, 0, 0x7f7f7f7f);
;       }
;     } else {
; #pragma unroll
;     for (int kk = 0; kk < 2; ++kk) {
;       const int ch = ((kk * 4 + g) ^ (li & 7)) << 4;
;       bf16x8 xf[MI], wf[4];
; #pragma unroll
;       for (int j = 0; j < 4; ++j) wf[j] = *(const bf16x8*)(smem + wrow + ((j & 1) * 16 + (j >> 1) * 64) * 128 + ch);
; #pragma unroll
;       for (int i = 0; i < MI; ++i) xf[i] = *(const bf16x8*)(smem + xrow + i * 2048 + ch);
; #pragma unroll
;       for (int i = 0; i < MI; ++i)
; #pragma unroll
;         for (int j = 0; j < 4; ++j) {
	v_mfma_f32_16x16x32_bf16 v[104:107], v[92:95], v[52:55], v[40:43]
	s_nop 2
	ds_read_b128 v[40:43], v137 offset:40960
	s_waitcnt lgkmcnt(0)
	v_mfma_f32_16x16x32_bf16 v[112:115], v[40:43], v[52:55], v[56:59]
	v_mfma_f32_16x16x32_bf16 v[116:119], v[92:95], v[100:103], v[60:63]
	v_mfma_f32_16x16x32_bf16 v[64:67], v[96:99], v[100:103], v[64:67]
	v_mfma_f32_16x16x32_bf16 v[68:71], v[40:43], v[100:103], v[68:71]
	v_mfma_f32_16x16x32_bf16 v[100:103], v[108:111], v[100:103], v[36:39]
	s_nop 2
	ds_read_b128 v[36:39], v0 offset:4096
	ds_read_b128 v[56:59], v0 offset:6144
	global_load_dwordx4 v[60:63], v[22:23], off offset:128
	s_waitcnt lgkmcnt(1)
	v_mfma_f32_16x16x32_bf16 v[80:83], v[92:95], v[36:39], v[80:83]
	v_mfma_f32_16x16x32_bf16 v[84:87], v[96:99], v[36:39], v[84:87]
	v_mfma_f32_16x16x32_bf16 v[88:91], v[40:43], v[36:39], v[88:91]
	v_mfma_f32_16x16x32_bf16 v[72:75], v[108:111], v[36:39], v[72:75]
	global_load_dwordx4 v[36:39], v[2:3], off offset:128
	s_nop 0
	global_load_dwordx4 v[120:123], v[120:121], off offset:128
	s_nop 0
	global_load_dwordx4 v[20:23], v[20:21], off offset:128
	v_mov_b32_e32 v2, v208
	s_waitcnt lgkmcnt(0)
	v_mfma_f32_16x16x32_bf16 v[92:95], v[92:95], v[56:59], v[24:27]
	s_nop 2
	global_load_dwordx4 v[24:27], v[126:127], off offset:128
	s_nop 0
	global_load_dwordx4 v[124:127], v[124:125], off offset:128
	s_nop 0
	global_load_dwordx4 v[128:131], v[128:129], off offset:128
	v_mfma_f32_16x16x32_bf16 v[48:51], v[96:99], v[52:55], v[48:51]
	v_mfma_f32_16x16x32_bf16 v[32:35], v[108:111], v[52:55], v[32:35]
	v_mfma_f32_16x16x32_bf16 v[52:55], v[96:99], v[56:59], v[28:31]
	s_nop 2
	global_load_dwordx4 v[28:31], v[132:133], off offset:128
	v_mfma_f32_16x16x32_bf16 v[40:43], v[40:43], v[56:59], v[44:47]
	s_barrier
	v_mfma_f32_16x16x32_bf16 v[44:47], v[108:111], v[56:59], v[76:79]
	s_waitcnt vmcnt(6)
	ds_write_b128 v134, v[36:39]
	ds_write_b128 v134, v[60:63] offset:4096
	s_waitcnt vmcnt(4)
	ds_write_b128 v134, v[20:23] offset:8192
	ds_write_b128 v134, v[120:123] offset:12288
	s_waitcnt vmcnt(2)
	ds_write_b128 v134, v[124:127] offset:32768
	ds_write_b128 v134, v[24:27] offset:36864
	s_waitcnt vmcnt(1)
	ds_write_b128 v134, v[128:131] offset:40960
	s_waitcnt vmcnt(0)
	ds_write_b128 v134, v[28:31] offset:45056
	s_waitcnt lgkmcnt(0)
	s_barrier
	ds_read_b128 v[76:79], v135 offset:32768
	ds_read_b128 v[96:99], v135 offset:34816
	ds_read_b128 v[20:23], v136
	ds_read_b128 v[24:27], v136 offset:2048
	s_waitcnt lgkmcnt(1)
	v_mfma_f32_16x16x32_bf16 v[56:59], v[76:79], v[20:23], v[104:107]
	s_nop 2
	ds_read_b128 v[104:107], v135 offset:40960
	ds_read_b128 v[108:111], v135 offset:43008
	v_mov_b32_e32 v120, v1
	v_mfma_f32_16x16x32_bf16 v[60:63], v[96:99], v[20:23], v[48:51]
	v_mov_b32_e32 v121, v1
	v_mov_b32_e32 v122, v1
	v_mov_b32_e32 v123, v1
	s_waitcnt lgkmcnt(0)
	v_mfma_f32_16x16x32_bf16 v[48:51], v[108:111], v[20:23], v[32:35]
	v_mov_b32_e32 v124, v1
	v_mov_b32_e32 v125, v1
	v_mov_b32_e32 v126, v1
	v_mfma_f32_16x16x32_bf16 v[32:35], v[96:99], v[24:27], v[64:67]
	v_mov_b32_e32 v127, v1
	v_mov_b32_e32 v128, v1
	v_mov_b32_e32 v129, v1
	v_mfma_f32_16x16x32_bf16 v[28:31], v[104:107], v[24:27], v[68:71]
	ds_read_b128 v[64:67], v136 offset:4096
	s_nop 1
	ds_read_b128 v[68:71], v136 offset:6144
	v_mov_b32_e32 v130, v1
	v_mov_b32_e32 v131, v1
	v_mfma_f32_16x16x32_bf16 v[112:115], v[104:107], v[20:23], v[112:115]
	v_mfma_f32_16x16x32_bf16 v[36:39], v[76:79], v[24:27], v[116:119]
	v_mfma_f32_16x16x32_bf16 v[24:27], v[108:111], v[24:27], v[100:103]
	s_nop 1
	v_mov_b32_e32 v116, v1
	v_mov_b32_e32 v117, v1
	v_mov_b32_e32 v118, v1
	s_waitcnt lgkmcnt(1)
	v_mfma_f32_16x16x32_bf16 v[20:23], v[76:79], v[64:67], v[80:83]
	v_mov_b32_e32 v119, v1
	v_mfma_f32_16x16x32_bf16 v[80:83], v[96:99], v[64:67], v[84:87]
	v_mfma_f32_16x16x32_bf16 v[84:87], v[104:107], v[64:67], v[88:91]
	v_mfma_f32_16x16x32_bf16 v[64:67], v[108:111], v[64:67], v[72:75]
	s_waitcnt lgkmcnt(0)
	v_mfma_f32_16x16x32_bf16 v[72:75], v[76:79], v[68:71], v[92:95]
	ds_read_b128 v[76:79], v137 offset:32768
	ds_read_b128 v[88:91], v137 offset:34816
	v_mfma_f32_16x16x32_bf16 v[52:55], v[96:99], v[68:71], v[52:55]
	v_mfma_f32_16x16x32_bf16 v[40:43], v[104:107], v[68:71], v[40:43]
	v_mfma_f32_16x16x32_bf16 v[44:47], v[108:111], v[68:71], v[44:47]
	ds_read_b128 v[68:71], v0
	ds_read_b128 v[92:95], v0 offset:2048
	ds_read_b128 v[96:99], v137 offset:40960
	ds_read_b128 v[100:103], v137 offset:43008
	s_waitcnt lgkmcnt(3)
	v_mfma_f32_16x16x32_bf16 v[56:59], v[76:79], v[68:71], v[56:59]
	v_mfma_f32_16x16x32_bf16 v[60:63], v[88:91], v[68:71], v[60:63]
	s_waitcnt lgkmcnt(1)
	v_mfma_f32_16x16x32_bf16 v[104:107], v[96:99], v[68:71], v[112:115]
	s_waitcnt lgkmcnt(0)
	v_mfma_f32_16x16x32_bf16 v[48:51], v[100:103], v[68:71], v[48:51]
	ds_read_b128 v[68:71], v0 offset:4096
	ds_read_b128 v[108:111], v0 offset:6144
	s_nop 0
	v_and_b32_e32 v0, 15, v2
	v_ashrrev_i32_e32 v3, 1, v2
	v_mfma_f32_16x16x32_bf16 v[36:39], v[76:79], v[92:95], v[36:39]
	s_nop 1
	v_mul_f32_e32 v48, 0x43800000, v48
	v_mul_f32_e32 v49, 0x43800000, v49
	v_cvt_pk_fp8_f32 v119, v48, v49
	v_mfma_f32_16x16x32_bf16 v[32:35], v[88:91], v[92:95], v[32:35]
	v_mul_f32_e32 v50, 0x43800000, v50
	s_nop 0
	v_mul_f32_e32 v36, 0x43800000, v36
	v_mul_f32_e32 v37, 0x43800000, v37
	v_mfma_f32_16x16x32_bf16 v[28:31], v[96:99], v[92:95], v[28:31]
	v_cvt_pk_fp8_f32 v120, v36, v37
	s_nop 1
	v_mul_f32_e32 v32, 0x43800000, v32
	v_mul_f32_e32 v33, 0x43800000, v33
	v_mfma_f32_16x16x32_bf16 v[24:27], v[100:103], v[92:95], v[24:27]
	v_lshrrev_b32_e32 v92, 1, v2
	v_lshrrev_b32_e32 v93, 2, v2
	v_and_or_b32 v2, v3, s29, v0
	v_and_b32_e32 v0, 32, v92
	v_or_b32_e32 v92, 16, v2
	v_or_b32_e32 v94, 32, v2
	v_or_b32_e32 v112, 48, v2
	v_and_or_b32 v0, v93, 12, v0
	v_ashrrev_i32_e32 v3, 31, v2
	v_ashrrev_i32_e32 v93, 31, v92
	v_ashrrev_i32_e32 v95, 31, v94
	v_ashrrev_i32_e32 v113, 31, v112
	s_waitcnt lgkmcnt(1)
; template <int MI>
; __device__ void gemm_tile_fp8out(const bf16_t* A, int lda, const bf16_t* B, int ldb, int K, unsigned char* C, int ldc, float mul, char* smem) {
;   f32x4 acc[MI][4];
;   gemm_core<MI, false>(A, lda, B, ldb, K, smem, acc);
;   EPI_COORDS
; #pragma unroll
;   for (int i = 0; i < MI; ++i)
; #pragma unroll
;     for (int j = 0; j < 4; ++j) {
;       int wd = __builtin_amdgcn_cvt_pk_fp8_f32(acc[i][j][0] * mul, acc[i][j][1] * mul, 0, false);
;       wd = __builtin_amdgcn_cvt_pk_fp8_f32(acc[i][j][2] * mul, acc[i][j][3] * mul, wd, true);
;       *(int*)(C + (size_t)MROW(i) * ldc + NCOL(j)) = wd;
;     }
; __global__ void __launch_bounds__(256, 2) fwd_kernel(P p) {
;     ...
;       const int qb = (layer == 0) ? 16384 : 49152, qe = (layer == 0) ? 49152 : 65536;
	v_mfma_f32_16x16x32_bf16 v[20:23], v[76:79], v[68:71], v[20:23]
	v_lshlrev_b64 v[2:3], 10, v[2:3]
	v_lshlrev_b64 v[92:93], 10, v[92:93]
	v_lshl_add_u64 v[2:3], s[0:1], 0, v[2:3]
	v_mfma_f32_16x16x32_bf16 v[80:83], v[88:91], v[68:71], v[80:83]
	v_lshl_add_u64 v[2:3], v[2:3], 0, v[0:1]
	v_mul_f32_e32 v28, 0x43800000, v28
	v_mul_f32_e32 v29, 0x43800000, v29
	v_mfma_f32_16x16x32_bf16 v[84:87], v[96:99], v[68:71], v[84:87]
	v_mul_f32_e32 v24, 0x43800000, v24
	v_mul_f32_e32 v25, 0x43800000, v25
	v_mul_f32_e32 v20, 0x43800000, v20
	v_mfma_f32_16x16x32_bf16 v[64:67], v[100:103], v[68:71], v[64:67]
	v_mul_f32_e32 v21, 0x43800000, v21
	v_mul_f32_e32 v80, 0x43800000, v80
	v_mul_f32_e32 v81, 0x43800000, v81
	s_waitcnt lgkmcnt(0)
	v_mfma_f32_16x16x32_bf16 v[68:71], v[76:79], v[108:111], v[72:75]
	v_lshl_add_u64 v[76:77], s[0:1], 0, v[92:93]
	v_lshl_add_u64 v[76:77], v[76:77], 0, v[0:1]
	v_mul_f32_e32 v78, 0x43800000, v105
	v_lshlrev_b64 v[72:73], 10, v[94:95]
	v_lshlrev_b64 v[74:75], 10, v[112:113]
	v_lshl_add_u64 v[72:73], s[0:1], 0, v[72:73]
	v_lshl_add_u64 v[74:75], s[0:1], 0, v[74:75]
	v_mfma_f32_16x16x32_bf16 v[52:55], v[88:91], v[108:111], v[52:55]
	v_lshl_add_u64 v[72:73], v[72:73], 0, v[0:1]
	v_lshl_add_u64 v[74:75], v[74:75], 0, v[0:1]
	v_mul_f32_e32 v0, 0x43800000, v56
	v_mfma_f32_16x16x32_bf16 v[40:43], v[96:99], v[108:111], v[40:43]
	v_mul_f32_e32 v56, 0x43800000, v57
	v_mul_f32_e32 v57, 0x43800000, v58
	v_mul_f32_e32 v58, 0x43800000, v59
	v_mfma_f32_16x16x32_bf16 v[44:47], v[100:103], v[108:111], v[44:47]
	v_mul_f32_e32 v59, 0x43800000, v60
	v_mul_f32_e32 v60, 0x43800000, v61
	v_cvt_pk_fp8_f32 v116, v0, v56
	v_mul_f32_e32 v61, 0x43800000, v62
	v_mul_f32_e32 v62, 0x43800000, v63
	v_mul_f32_e32 v63, 0x43800000, v104
	v_cvt_pk_fp8_f32 v117, v59, v60
	v_cvt_pk_fp8_f32 v118, v63, v78
	v_mul_f32_e32 v84, 0x43800000, v84
	v_mul_f32_e32 v85, 0x43800000, v85
	v_mul_f32_e32 v64, 0x43800000, v64
	v_mul_f32_e32 v65, 0x43800000, v65
	v_mul_f32_e32 v68, 0x43800000, v68
	v_mul_f32_e32 v69, 0x43800000, v69
	v_mul_f32_e32 v52, 0x43800000, v52
	v_mul_f32_e32 v53, 0x43800000, v53
	v_mul_f32_e32 v40, 0x43800000, v40
	v_mul_f32_e32 v41, 0x43800000, v41
	v_mul_f32_e32 v44, 0x43800000, v44
	v_mul_f32_e32 v45, 0x43800000, v45
	v_cvt_pk_fp8_f32 v121, v32, v33
	v_cvt_pk_fp8_f32 v122, v28, v29
	v_cvt_pk_fp8_f32 v123, v24, v25
	v_cvt_pk_fp8_f32 v124, v20, v21
	v_cvt_pk_fp8_f32 v125, v80, v81
	v_cvt_pk_fp8_f32 v126, v84, v85
	v_cvt_pk_fp8_f32 v127, v64, v65
	v_cvt_pk_fp8_f32 v128, v68, v69
	v_cvt_pk_fp8_f32 v129, v52, v53
	v_cvt_pk_fp8_f32 v130, v40, v41
	v_cvt_pk_fp8_f32 v131, v44, v45
	v_cvt_pk_fp8_f32 v116, v57, v58 op_sel:[0,0,1]
	v_mul_f32_e32 v79, 0x43800000, v106
	v_mul_f32_e32 v88, 0x43800000, v107
	v_cvt_pk_fp8_f32 v117, v61, v62 op_sel:[0,0,1]
	v_mul_f32_e32 v51, 0x43800000, v51
	v_cvt_pk_fp8_f32 v118, v79, v88 op_sel:[0,0,1]
	v_mul_f32_e32 v38, 0x43800000, v38
	v_mul_f32_e32 v39, 0x43800000, v39
	v_mul_f32_e32 v34, 0x43800000, v34
	v_mul_f32_e32 v35, 0x43800000, v35
	v_mul_f32_e32 v30, 0x43800000, v30
	v_mul_f32_e32 v31, 0x43800000, v31
	v_mul_f32_e32 v26, 0x43800000, v26
	v_mul_f32_e32 v27, 0x43800000, v27
	v_mul_f32_e32 v22, 0x43800000, v22
	v_mul_f32_e32 v23, 0x43800000, v23
	v_mul_f32_e32 v82, 0x43800000, v82
	v_mul_f32_e32 v83, 0x43800000, v83
	v_mul_f32_e32 v86, 0x43800000, v86
	v_mul_f32_e32 v87, 0x43800000, v87
	v_mul_f32_e32 v66, 0x43800000, v66
	v_mul_f32_e32 v67, 0x43800000, v67
	v_mul_f32_e32 v70, 0x43800000, v70
	v_mul_f32_e32 v71, 0x43800000, v71
	v_mul_f32_e32 v54, 0x43800000, v54
	v_mul_f32_e32 v55, 0x43800000, v55
	v_mul_f32_e32 v42, 0x43800000, v42
	v_mul_f32_e32 v43, 0x43800000, v43
	v_mul_f32_e32 v46, 0x43800000, v46
	v_mul_f32_e32 v47, 0x43800000, v47
	v_cvt_pk_fp8_f32 v119, v50, v51 op_sel:[0,0,1]
	v_cvt_pk_fp8_f32 v120, v38, v39 op_sel:[0,0,1]
	v_cvt_pk_fp8_f32 v121, v34, v35 op_sel:[0,0,1]
	v_cvt_pk_fp8_f32 v122, v30, v31 op_sel:[0,0,1]
	v_cvt_pk_fp8_f32 v123, v26, v27 op_sel:[0,0,1]
	v_cvt_pk_fp8_f32 v124, v22, v23 op_sel:[0,0,1]
	v_cvt_pk_fp8_f32 v125, v82, v83 op_sel:[0,0,1]
	v_cvt_pk_fp8_f32 v126, v86, v87 op_sel:[0,0,1]
	v_cvt_pk_fp8_f32 v127, v66, v67 op_sel:[0,0,1]
	v_cvt_pk_fp8_f32 v128, v70, v71 op_sel:[0,0,1]
	v_cvt_pk_fp8_f32 v129, v54, v55 op_sel:[0,0,1]
	v_cvt_pk_fp8_f32 v130, v42, v43 op_sel:[0,0,1]
	v_cvt_pk_fp8_f32 v131, v46, v47 op_sel:[0,0,1]
	global_store_dword v[2:3], v116, off
	global_store_dword v[2:3], v117, off offset:16
	global_store_dword v[2:3], v118, off offset:64
	global_store_dword v[2:3], v119, off offset:80
	global_store_dword v[76:77], v120, off
	global_store_dword v[76:77], v121, off offset:16
	global_store_dword v[76:77], v122, off offset:64
	global_store_dword v[76:77], v123, off offset:80
	global_store_dword v[72:73], v124, off
	global_store_dword v[72:73], v125, off offset:16
	global_store_dword v[72:73], v126, off offset:64
	global_store_dword v[72:73], v127, off offset:80
	global_store_dword v[74:75], v128, off
	global_store_dword v[74:75], v129, off offset:16
	global_store_dword v[74:75], v130, off offset:64
	global_store_dword v[74:75], v131, off offset:80
	s_cbranch_scc1 .LBB0_385
	s_mov_b32 s19, 0xc000
	s_movk_i32 s36, 0

; __device__ __forceinline__ int otid() { int t = threadIdx.x; asm volatile("" : "+v"(t)); return t; }
; __device__ void quant_rows(const float* src, unsigned char* dst, float* scales, int row_begin, int nrows) {
;   const int tid_ = otid();
;   const int lane = tid_ & 63, w = tid_ >> 6;
;   for (int row = row_begin + blockIdx.x * 4 + w; row < nrows; row += gridDim.x * 4) {
;     const f32x4* sp = (const f32x4*)(src + (size_t)row * 1024) + lane * 4;
;     f32x4 v[4];
;     float am = 0.f;
; #pragma unroll
;     for (int k = 0; k < 4; ++k) {
;       v[k] = sp[k];
;       am = fmaxf(am, fmaxf(fmaxf(fabsf(v[k].x), fabsf(v[k].y)), fmaxf(fabsf(v[k].z), fabsf(v[k].w))));
;     }
;     am = fmaxf(am, __shfl_xor(am, 1)); am = fmaxf(am, __shfl_xor(am, 2)); am = fmaxf(am, __shfl_xor(am, 4));
;     am = fmaxf(am, __shfl_xor(am, 8)); am = fmaxf(am, __shfl_xor(am, 16)); am = fmaxf(am, __shfl_xor(am, 32));
;     const float sc = am > 0.f ? 6.f / am : 1.f;
;     u32x2 o;
; #pragma unroll
;     for (int k = 0; k < 2; ++k) {
;       unsigned wd = 0u;
;       wd = __builtin_amdgcn_cvt_scalef32_pk_fp4_f32(wd, v[2 * k].x * sc, v[2 * k].y * sc, 1.0f, 0);
;       wd = __builtin_amdgcn_cvt_scalef32_pk_fp4_f32(wd, v[2 * k].z * sc, v[2 * k].w * sc, 1.0f, 1);
;       wd = __builtin_amdgcn_cvt_scalef32_pk_fp4_f32(wd, v[2 * k + 1].x * sc, v[2 * k + 1].y * sc, 1.0f, 2);
;       wd = __builtin_amdgcn_cvt_scalef32_pk_fp4_f32(wd, v[2 * k + 1].z * sc, v[2 * k + 1].w * sc, 1.0f, 3);
;       o[k] = wd;
;     }
;     ((u32x2*)(dst + (size_t)row * 512))[lane] = o;
;     if (lane == 0) scales[row] = am > 0.f ? am * (1.f / 6.f) : 1.f;
;   }
.LBB0_443:
	v_ashrrev_i32_e32 v3, 31, v2
	v_lshlrev_b64 v[30:31], 12, v[2:3]
	s_waitcnt vmcnt(14)
	v_lshl_add_u64 v[42:43], v[20:21], 0, v[30:31]
	s_mul_i32 s57, s86, 1
	v_add_u32_e32 v200, s57, v2
	v_cmp_gt_i32_e32 vcc, s19, v200
	s_lshl_b32 s57, s57, 12
	v_mov_b32_e32 v200, s57
	v_cndmask_b32_e32 v200, 0, v200, vcc
	v_add_co_u32_e32 v194, vcc, v200, v42
	s_nop 1
	v_addc_co_u32_e32 v195, vcc, 0, v43, vcc
	global_load_dwordx4 v[30:33], v[42:43], off
	global_load_dwordx4 v[34:37], v[42:43], off offset:16
	global_load_dwordx4 v[38:41], v[42:43], off offset:32
	s_nop 0
	global_load_dwordx4 v[42:45], v[42:43], off offset:48
	global_load_dwordx4 v[196:199], v[194:195], off
	global_load_dwordx4 v[196:199], v[194:195], off offset:16
	global_load_dwordx4 v[196:199], v[194:195], off offset:32
	global_load_dwordx4 v[196:199], v[194:195], off offset:48
	s_mov_b32 s23, 0x40c00000
	s_waitcnt vmcnt(7)
	v_max_f32_e64 v0, |v33|, |v33|
	v_max_f32_e64 v46, |v32|, |v32|
	s_waitcnt vmcnt(6)
	v_max_f32_e64 v47, |v37|, |v37|
	v_max_f32_e64 v48, |v36|, |v36|
	s_waitcnt vmcnt(5)
	v_max_f32_e64 v49, |v41|, |v41|
	v_max_f32_e64 v50, |v40|, |v40|
	s_waitcnt vmcnt(4)
	v_max_f32_e64 v51, |v45|, |v45|
	v_max_f32_e64 v52, |v44|, |v44|
	v_max_f32_e32 v0, v46, v0
	v_max_f32_e32 v46, v48, v47
	v_max_f32_e32 v47, v50, v49
	v_max_f32_e32 v48, v52, v51
	v_max3_f32 v0, |v30|, |v31|, v0
	v_max3_f32 v46, |v34|, |v35|, v46
	v_max3_f32 v47, |v38|, |v39|, v47
	v_max3_f32 v48, |v42|, |v43|, v48
	v_max3_f32 v0, v0, 0, v46
	v_max3_f32 v0, v0, v47, v48
	ds_bpermute_b32 v46, v24, v0
	v_mov_b32_e32 v47, v1
	s_waitcnt lgkmcnt(0)
	v_max_f32_e32 v46, v46, v46
	v_max_f32_e32 v0, v0, v46
	ds_bpermute_b32 v46, v25, v0
	s_waitcnt lgkmcnt(0)
	v_max_f32_e32 v46, v46, v46
	v_max_f32_e32 v0, v0, v46
	ds_bpermute_b32 v46, v26, v0
	s_waitcnt lgkmcnt(0)
	v_max_f32_e32 v46, v46, v46
	v_max_f32_e32 v0, v0, v46
	ds_bpermute_b32 v46, v27, v0
	s_waitcnt lgkmcnt(0)
	v_max_f32_e32 v46, v46, v46
	v_max_f32_e32 v0, v0, v46
	ds_bpermute_b32 v46, v28, v0
	s_waitcnt lgkmcnt(0)
	v_max_f32_e32 v46, v46, v46
	v_max_f32_e32 v0, v0, v46
	ds_bpermute_b32 v48, v29, v0
	v_mov_b32_e32 v46, v1
	s_waitcnt lgkmcnt(0)
	v_max_f32_e32 v48, v48, v48
	v_max_f32_e32 v0, v0, v48
	v_div_scale_f32 v50, s[20:21], v0, v0, s23
	v_rcp_f32_e32 v51, v50
	v_div_scale_f32 v52, vcc, s23, v0, s23
	v_lshlrev_b64 v[48:49], 9, v[2:3]
	v_fma_f32 v53, -v50, v51, 1.0
	v_fmac_f32_e32 v51, v53, v51
	v_mul_f32_e32 v53, v52, v51
	v_fma_f32 v54, -v50, v53, v52
	v_fmac_f32_e32 v53, v54, v51
	v_fma_f32 v50, -v50, v53, v52
	v_div_fmas_f32 v50, v50, v51, v53
	v_div_fixup_f32 v50, v50, v0, s23
	v_cmp_lt_f32_e32 vcc, 0, v0
	s_nop 1
	v_cndmask_b32_e32 v50, 1.0, v50, vcc
	v_mul_f32_e32 v30, v30, v50
	v_mul_f32_e32 v31, v31, v50
	v_mul_f32_e32 v38, v38, v50
	v_mul_f32_e32 v39, v39, v50
	v_mul_f32_e32 v32, v32, v50
	v_mul_f32_e32 v33, v33, v50
	v_mul_f32_e32 v40, v40, v50
	v_mul_f32_e32 v41, v41, v50
	v_cvt_scalef32_pk_fp4_f32 v46, v30, v31, 1.0
	v_cvt_scalef32_pk_fp4_f32 v47, v38, v39, 1.0
	v_mul_f32_e32 v34, v34, v50
	v_mul_f32_e32 v35, v35, v50
	v_mul_f32_e32 v42, v42, v50
	v_mul_f32_e32 v43, v43, v50
	v_cvt_scalef32_pk_fp4_f32 v46, v32, v33, 1.0 op_sel:[0,0,1,0]
	v_cvt_scalef32_pk_fp4_f32 v47, v40, v41, 1.0 op_sel:[0,0,1,0]
	v_mul_f32_e32 v36, v36, v50
	v_mul_f32_e32 v37, v37, v50
	v_mul_f32_e32 v44, v44, v50
	v_mul_f32_e32 v45, v45, v50
	v_cvt_scalef32_pk_fp4_f32 v46, v34, v35, 1.0 op_sel:[0,0,0,1]
	v_cvt_scalef32_pk_fp4_f32 v47, v42, v43, 1.0 op_sel:[0,0,0,1]
	v_cvt_scalef32_pk_fp4_f32 v46, v36, v37, 1.0 op_sel:[0,0,1,1]
	v_cvt_scalef32_pk_fp4_f32 v47, v44, v45, 1.0 op_sel:[0,0,1,1]
	v_lshl_add_u64 v[30:31], v[22:23], 0, v[48:49]
	global_store_dwordx2 v[30:31], v[46:47], off
	s_and_saveexec_b64 s[20:21], s[0:1]
	s_cbranch_execz .LBB0_442
	v_mul_f32_e32 v0, 0x3e2aaaab, v0
	v_cndmask_b32_e32 v0, 1.0, v0, vcc
	v_lshl_add_u64 v[30:31], v[2:3], 2, s[8:9]
	global_store_dword v[30:31], v0, off
	s_branch .LBB0_442

; __device__ __forceinline__ int otid() { int t = threadIdx.x; asm volatile("" : "+v"(t)); return t; }
; __device__ void quant_rows(const float* src, unsigned char* dst, float* scales, int row_begin, int nrows) {
;   const int tid_ = otid();
;   const int lane = tid_ & 63, w = tid_ >> 6;
;   for (int row = row_begin + blockIdx.x * 4 + w; row < nrows; row += gridDim.x * 4) {
;     const f32x4* sp = (const f32x4*)(src + (size_t)row * 1024) + lane * 4;
;     f32x4 v[4];
;     float am = 0.f;
; #pragma unroll
;     for (int k = 0; k < 4; ++k) {
;       v[k] = sp[k];
;       am = fmaxf(am, fmaxf(fmaxf(fabsf(v[k].x), fabsf(v[k].y)), fmaxf(fabsf(v[k].z), fabsf(v[k].w))));
;     }
;     am = fmaxf(am, __shfl_xor(am, 1)); am = fmaxf(am, __shfl_xor(am, 2)); am = fmaxf(am, __shfl_xor(am, 4));
;     am = fmaxf(am, __shfl_xor(am, 8)); am = fmaxf(am, __shfl_xor(am, 16)); am = fmaxf(am, __shfl_xor(am, 32));
;     const float sc = am > 0.f ? 6.f / am : 1.f;
;     u32x2 o;
; #pragma unroll
;     for (int k = 0; k < 2; ++k) {
;       unsigned wd = 0u;
;       wd = __builtin_amdgcn_cvt_scalef32_pk_fp4_f32(wd, v[2 * k].x * sc, v[2 * k].y * sc, 1.0f, 0);
;       wd = __builtin_amdgcn_cvt_scalef32_pk_fp4_f32(wd, v[2 * k].z * sc, v[2 * k].w * sc, 1.0f, 1);
;       wd = __builtin_amdgcn_cvt_scalef32_pk_fp4_f32(wd, v[2 * k + 1].x * sc, v[2 * k + 1].y * sc, 1.0f, 2);
;       wd = __builtin_amdgcn_cvt_scalef32_pk_fp4_f32(wd, v[2 * k + 1].z * sc, v[2 * k + 1].w * sc, 1.0f, 3);
;       o[k] = wd;
;     }
;     ((u32x2*)(dst + (size_t)row * 512))[lane] = o;
;     if (lane == 0) scales[row] = am > 0.f ? am * (1.f / 6.f) : 1.f;
;   }
.LBB0_448:
	v_ashrrev_i32_e32 v3, 31, v2
	v_lshlrev_b64 v[30:31], 12, v[2:3]
	s_waitcnt vmcnt(14)
	v_lshl_add_u64 v[42:43], v[20:21], 0, v[30:31]
	s_mul_i32 s57, s86, 1
	v_add_u32_e32 v200, s57, v2
	v_cmp_gt_i32_e32 vcc, s19, v200
	s_lshl_b32 s57, s57, 12
	v_mov_b32_e32 v200, s57
	v_cndmask_b32_e32 v200, 0, v200, vcc
	v_add_co_u32_e32 v194, vcc, v200, v42
	s_nop 1
	v_addc_co_u32_e32 v195, vcc, 0, v43, vcc
	global_load_dwordx4 v[30:33], v[42:43], off
	global_load_dwordx4 v[34:37], v[42:43], off offset:16
	global_load_dwordx4 v[38:41], v[42:43], off offset:32
	s_nop 0
	global_load_dwordx4 v[42:45], v[42:43], off offset:48
	global_load_dwordx4 v[196:199], v[194:195], off
	global_load_dwordx4 v[196:199], v[194:195], off offset:16
	global_load_dwordx4 v[196:199], v[194:195], off offset:32
	global_load_dwordx4 v[196:199], v[194:195], off offset:48
	s_mov_b32 s22, 0x40c00000
	s_waitcnt vmcnt(7)
	v_max_f32_e64 v0, |v33|, |v33|
	v_max_f32_e64 v46, |v32|, |v32|
	s_waitcnt vmcnt(6)
	v_max_f32_e64 v47, |v37|, |v37|
	v_max_f32_e64 v48, |v36|, |v36|
	s_waitcnt vmcnt(5)
	v_max_f32_e64 v49, |v41|, |v41|
	v_max_f32_e64 v50, |v40|, |v40|
	s_waitcnt vmcnt(4)
	v_max_f32_e64 v51, |v45|, |v45|
	v_max_f32_e64 v52, |v44|, |v44|
	v_max_f32_e32 v0, v46, v0
	v_max_f32_e32 v46, v48, v47
	v_max_f32_e32 v47, v50, v49
	v_max_f32_e32 v48, v52, v51
	v_max3_f32 v0, |v30|, |v31|, v0
	v_max3_f32 v46, |v34|, |v35|, v46
	v_max3_f32 v47, |v38|, |v39|, v47
	v_max3_f32 v48, |v42|, |v43|, v48
	v_max3_f32 v0, v0, 0, v46
	v_max3_f32 v0, v0, v47, v48
	ds_bpermute_b32 v46, v24, v0
	v_mov_b32_e32 v47, v1
	s_waitcnt lgkmcnt(0)
	v_max_f32_e32 v46, v46, v46
	v_max_f32_e32 v0, v0, v46
	ds_bpermute_b32 v46, v25, v0
	s_waitcnt lgkmcnt(0)
	v_max_f32_e32 v46, v46, v46
	v_max_f32_e32 v0, v0, v46
	ds_bpermute_b32 v46, v26, v0
	s_waitcnt lgkmcnt(0)
	v_max_f32_e32 v46, v46, v46
	v_max_f32_e32 v0, v0, v46
	ds_bpermute_b32 v46, v27, v0
	s_waitcnt lgkmcnt(0)
	v_max_f32_e32 v46, v46, v46
	v_max_f32_e32 v0, v0, v46
	ds_bpermute_b32 v46, v28, v0
	s_waitcnt lgkmcnt(0)
	v_max_f32_e32 v46, v46, v46
	v_max_f32_e32 v0, v0, v46
	ds_bpermute_b32 v48, v29, v0
	v_mov_b32_e32 v46, v1
	s_waitcnt lgkmcnt(0)
	v_max_f32_e32 v48, v48, v48
	v_max_f32_e32 v0, v0, v48
	v_div_scale_f32 v50, s[20:21], v0, v0, s22
	v_rcp_f32_e32 v51, v50
	v_div_scale_f32 v52, vcc, s22, v0, s22
	v_lshlrev_b64 v[48:49], 9, v[2:3]
	v_fma_f32 v53, -v50, v51, 1.0
	v_fmac_f32_e32 v51, v53, v51
	v_mul_f32_e32 v53, v52, v51
	v_fma_f32 v54, -v50, v53, v52
	v_fmac_f32_e32 v53, v54, v51
	v_fma_f32 v50, -v50, v53, v52
	v_div_fmas_f32 v50, v50, v51, v53
	v_div_fixup_f32 v50, v50, v0, s22
	v_cmp_lt_f32_e32 vcc, 0, v0
	s_nop 1
	v_cndmask_b32_e32 v50, 1.0, v50, vcc
	v_mul_f32_e32 v30, v30, v50
	v_mul_f32_e32 v31, v31, v50
	v_mul_f32_e32 v38, v38, v50
	v_mul_f32_e32 v39, v39, v50
	v_mul_f32_e32 v32, v32, v50
	v_mul_f32_e32 v33, v33, v50
	v_mul_f32_e32 v40, v40, v50
	v_mul_f32_e32 v41, v41, v50
	v_cvt_scalef32_pk_fp4_f32 v46, v30, v31, 1.0
	v_cvt_scalef32_pk_fp4_f32 v47, v38, v39, 1.0
	v_mul_f32_e32 v34, v34, v50
	v_mul_f32_e32 v35, v35, v50
	v_mul_f32_e32 v42, v42, v50
	v_mul_f32_e32 v43, v43, v50
	v_cvt_scalef32_pk_fp4_f32 v46, v32, v33, 1.0 op_sel:[0,0,1,0]
	v_cvt_scalef32_pk_fp4_f32 v47, v40, v41, 1.0 op_sel:[0,0,1,0]
	v_mul_f32_e32 v36, v36, v50
	v_mul_f32_e32 v37, v37, v50
	v_mul_f32_e32 v44, v44, v50
	v_mul_f32_e32 v45, v45, v50
	v_cvt_scalef32_pk_fp4_f32 v46, v34, v35, 1.0 op_sel:[0,0,0,1]
	v_cvt_scalef32_pk_fp4_f32 v47, v42, v43, 1.0 op_sel:[0,0,0,1]
	v_cvt_scalef32_pk_fp4_f32 v46, v36, v37, 1.0 op_sel:[0,0,1,1]
	v_cvt_scalef32_pk_fp4_f32 v47, v44, v45, 1.0 op_sel:[0,0,1,1]
	v_lshl_add_u64 v[30:31], v[22:23], 0, v[48:49]
	global_store_dwordx2 v[30:31], v[46:47], off
	s_and_saveexec_b64 s[20:21], s[0:1]
	s_cbranch_execz .LBB0_447
	v_mul_f32_e32 v0, 0x3e2aaaab, v0
	v_cndmask_b32_e32 v0, 1.0, v0, vcc
	v_lshl_add_u64 v[30:31], v[2:3], 2, s[8:9]
	global_store_dword v[30:31], v0, off
	s_branch .LBB0_447

; __device__ __forceinline__ int otid() { int t = threadIdx.x; asm volatile("" : "+v"(t)); return t; }
; __device__ void quant_rows(const float* src, unsigned char* dst, float* scales, int row_begin, int nrows) {
;   const int tid_ = otid();
;   const int lane = tid_ & 63, w = tid_ >> 6;
;   for (int row = row_begin + blockIdx.x * 4 + w; row < nrows; row += gridDim.x * 4) {
;     const f32x4* sp = (const f32x4*)(src + (size_t)row * 1024) + lane * 4;
;     f32x4 v[4];
;     float am = 0.f;
; #pragma unroll
;     for (int k = 0; k < 4; ++k) {
;       v[k] = sp[k];
;       am = fmaxf(am, fmaxf(fmaxf(fabsf(v[k].x), fabsf(v[k].y)), fmaxf(fabsf(v[k].z), fabsf(v[k].w))));
;     }
;     am = fmaxf(am, __shfl_xor(am, 1)); am = fmaxf(am, __shfl_xor(am, 2)); am = fmaxf(am, __shfl_xor(am, 4));
;     am = fmaxf(am, __shfl_xor(am, 8)); am = fmaxf(am, __shfl_xor(am, 16)); am = fmaxf(am, __shfl_xor(am, 32));
;     const float sc = am > 0.f ? 6.f / am : 1.f;
;     u32x2 o;
; #pragma unroll
;     for (int k = 0; k < 2; ++k) {
;       unsigned wd = 0u;
;       wd = __builtin_amdgcn_cvt_scalef32_pk_fp4_f32(wd, v[2 * k].x * sc, v[2 * k].y * sc, 1.0f, 0);
;       wd = __builtin_amdgcn_cvt_scalef32_pk_fp4_f32(wd, v[2 * k].z * sc, v[2 * k].w * sc, 1.0f, 1);
;       wd = __builtin_amdgcn_cvt_scalef32_pk_fp4_f32(wd, v[2 * k + 1].x * sc, v[2 * k + 1].y * sc, 1.0f, 2);
;       wd = __builtin_amdgcn_cvt_scalef32_pk_fp4_f32(wd, v[2 * k + 1].z * sc, v[2 * k + 1].w * sc, 1.0f, 3);
;       o[k] = wd;
;     }
;     ((u32x2*)(dst + (size_t)row * 512))[lane] = o;
;     if (lane == 0) scales[row] = am > 0.f ? am * (1.f / 6.f) : 1.f;
;   }
.LBB0_641:
	v_ashrrev_i32_e32 v3, 31, v2
	v_lshlrev_b64 v[30:31], 12, v[2:3]
	s_waitcnt vmcnt(14)
	v_lshl_add_u64 v[42:43], v[20:21], 0, v[30:31]
	s_mul_i32 s57, s86, 1
	v_add_u32_e32 v200, s57, v2
	v_cmp_gt_i32_e32 vcc, s19, v200
	s_lshl_b32 s57, s57, 12
	v_mov_b32_e32 v200, s57
	v_cndmask_b32_e32 v200, 0, v200, vcc
	v_add_co_u32_e32 v194, vcc, v200, v42
	s_nop 1
	v_addc_co_u32_e32 v195, vcc, 0, v43, vcc
	global_load_dwordx4 v[30:33], v[42:43], off
	global_load_dwordx4 v[34:37], v[42:43], off offset:16
	global_load_dwordx4 v[38:41], v[42:43], off offset:32
	s_nop 0
	global_load_dwordx4 v[42:45], v[42:43], off offset:48
	global_load_dwordx4 v[196:199], v[194:195], off
	global_load_dwordx4 v[196:199], v[194:195], off offset:16
	global_load_dwordx4 v[196:199], v[194:195], off offset:32
	global_load_dwordx4 v[196:199], v[194:195], off offset:48
	s_mov_b32 s24, 0x40c00000
	s_waitcnt vmcnt(7)
	v_max_f32_e64 v0, |v33|, |v33|
	v_max_f32_e64 v46, |v32|, |v32|
	s_waitcnt vmcnt(6)
	v_max_f32_e64 v47, |v37|, |v37|
	v_max_f32_e64 v48, |v36|, |v36|
	s_waitcnt vmcnt(5)
	v_max_f32_e64 v49, |v41|, |v41|
	v_max_f32_e64 v50, |v40|, |v40|
	s_waitcnt vmcnt(4)
	v_max_f32_e64 v51, |v45|, |v45|
	v_max_f32_e64 v52, |v44|, |v44|
	v_max_f32_e32 v0, v46, v0
	v_max_f32_e32 v46, v48, v47
	v_max_f32_e32 v47, v50, v49
	v_max_f32_e32 v48, v52, v51
	v_max3_f32 v0, |v30|, |v31|, v0
	v_max3_f32 v46, |v34|, |v35|, v46
	v_max3_f32 v47, |v38|, |v39|, v47
	v_max3_f32 v48, |v42|, |v43|, v48
	v_max3_f32 v0, v0, 0, v46
	v_max3_f32 v0, v0, v47, v48
	ds_bpermute_b32 v46, v24, v0
	v_mov_b32_e32 v47, v1
	s_waitcnt lgkmcnt(0)
	v_max_f32_e32 v46, v46, v46
	v_max_f32_e32 v0, v0, v46
	ds_bpermute_b32 v46, v25, v0
	s_waitcnt lgkmcnt(0)
	v_max_f32_e32 v46, v46, v46
	v_max_f32_e32 v0, v0, v46
	ds_bpermute_b32 v46, v26, v0
	s_waitcnt lgkmcnt(0)
	v_max_f32_e32 v46, v46, v46
	v_max_f32_e32 v0, v0, v46
	ds_bpermute_b32 v46, v27, v0
	s_waitcnt lgkmcnt(0)
	v_max_f32_e32 v46, v46, v46
	v_max_f32_e32 v0, v0, v46
	ds_bpermute_b32 v46, v28, v0
	s_waitcnt lgkmcnt(0)
	v_max_f32_e32 v46, v46, v46
	v_max_f32_e32 v0, v0, v46
	ds_bpermute_b32 v48, v29, v0
	v_mov_b32_e32 v46, v1
	s_waitcnt lgkmcnt(0)
	v_max_f32_e32 v48, v48, v48
	v_max_f32_e32 v0, v0, v48
	v_div_scale_f32 v50, s[22:23], v0, v0, s24
	v_rcp_f32_e32 v51, v50
	v_div_scale_f32 v52, vcc, s24, v0, s24
	v_lshlrev_b64 v[48:49], 9, v[2:3]
	v_fma_f32 v53, -v50, v51, 1.0
	v_fmac_f32_e32 v51, v53, v51
	v_mul_f32_e32 v53, v52, v51
	v_fma_f32 v54, -v50, v53, v52
	v_fmac_f32_e32 v53, v54, v51
	v_fma_f32 v50, -v50, v53, v52
	v_div_fmas_f32 v50, v50, v51, v53
	v_div_fixup_f32 v50, v50, v0, s24
	v_cmp_lt_f32_e32 vcc, 0, v0
	s_nop 1
	v_cndmask_b32_e32 v50, 1.0, v50, vcc
	v_mul_f32_e32 v30, v30, v50
	v_mul_f32_e32 v31, v31, v50
	v_mul_f32_e32 v38, v38, v50
	v_mul_f32_e32 v39, v39, v50
	v_mul_f32_e32 v32, v32, v50
	v_mul_f32_e32 v33, v33, v50
	v_mul_f32_e32 v40, v40, v50
	v_mul_f32_e32 v41, v41, v50
	v_cvt_scalef32_pk_fp4_f32 v46, v30, v31, 1.0
	v_cvt_scalef32_pk_fp4_f32 v47, v38, v39, 1.0
	v_mul_f32_e32 v34, v34, v50
	v_mul_f32_e32 v35, v35, v50
	v_mul_f32_e32 v42, v42, v50
	v_mul_f32_e32 v43, v43, v50
	v_cvt_scalef32_pk_fp4_f32 v46, v32, v33, 1.0 op_sel:[0,0,1,0]
	v_cvt_scalef32_pk_fp4_f32 v47, v40, v41, 1.0 op_sel:[0,0,1,0]
	v_mul_f32_e32 v36, v36, v50
	v_mul_f32_e32 v37, v37, v50
	v_mul_f32_e32 v44, v44, v50
	v_mul_f32_e32 v45, v45, v50
	v_cvt_scalef32_pk_fp4_f32 v46, v34, v35, 1.0 op_sel:[0,0,0,1]
	v_cvt_scalef32_pk_fp4_f32 v47, v42, v43, 1.0 op_sel:[0,0,0,1]
	v_cvt_scalef32_pk_fp4_f32 v46, v36, v37, 1.0 op_sel:[0,0,1,1]
	v_cvt_scalef32_pk_fp4_f32 v47, v44, v45, 1.0 op_sel:[0,0,1,1]
	v_lshl_add_u64 v[30:31], v[22:23], 0, v[48:49]
	global_store_dwordx2 v[30:31], v[46:47], off
	s_and_saveexec_b64 s[22:23], s[0:1]
	s_cbranch_execz .LBB0_640
	v_mul_f32_e32 v0, 0x3e2aaaab, v0
	v_cndmask_b32_e32 v0, 1.0, v0, vcc
	v_lshl_add_u64 v[30:31], v[2:3], 2, s[8:9]
	global_store_dword v[30:31], v0, off
	s_branch .LBB0_640
